# GU epilogue: row rstd precomputed in K-loop via LDS table instead of serialized rss loads after vmcnt(0)
# speedup vs baseline: 1.0051x; 1.0051x over previous
; #define PG8_STAGE(bufoff, gbase, voff) do { _Pragma("unroll") for (int _i = 0; _i < 2; ++_i) \
;         __builtin_amdgcn_global_load_lds((const unsigned*)((const char*)(gbase) + (voff)[_i]), (LAS unsigned*)(lds + (bufoff) + ldsw + _i * 8192), 16, 0, 0); } while (0)
; #define PG8_WAIT_V(n) asm volatile("s_waitcnt vmcnt(" #n ")" ::: "memory")
; #define PG8_BAR __builtin_amdgcn_s_barrier()
; template <class Epi>
; DI void gemm_phase(LAS unsigned char* lds, const int tid, const Gemm g, const StaticOrder& S, const Epi& E) {
;     const int wid = __builtin_amdgcn_readfirstlane(tid >> 6), lane = tid & 63, wr = wid >> 2, wc = wid & 3, fr = lane & 15, fq = lane >> 4;
;     const int K = g.K, nt = K / BK, lda = g.lda;
;     unsigned voffA[2], voffB[2];
; #pragma unroll
;     for (int i = 0; i < 2; ++i) { int R, C; stage_rc(tid * 16 + i * 8192, R, C); const int Rb = (R & ~31) + perm32(R & 31);
;         voffA[i] = (unsigned)(R * lda + C) * 2u; voffB[i] = (unsigned)(Rb * K + C) * 2u; }
;     const size_t kstep = (size_t)(BK * 2);
;     const size_t hstepA = (size_t)HALF * lda * 2, hstepB = (size_t)HALF * K * 2;
;     const size_t tstepA = 2 * hstepA, tstepB = 2 * hstepB;
;     const unsigned ldsw = (unsigned)wid * 1024u;
;     const int aoff = lds_byte(wr * 64 + fr, fq * 8), boff = lds_byte(wc * 32 + fr, fq * 8);
;     ...
;     Unit cur, nxt; int ui = 0;
;     if (!S.next(0, cur)) return;
;     f32x4 acc[2][2][4][2];
; #pragma unroll
;     for (int a = 0; a < 2; ++a)
; #pragma unroll
;         for (int b = 0; b < 2; ++b)
; #pragma unroll
;             for (int m = 0; m < 4; ++m)
; #pragma unroll
;                 for (int n = 0; n < 2; ++n) acc[a][b][m][n] = (f32x4){0.f, 0.f, 0.f, 0.f};
;     bf16x8 At[4][2], B0[2][2], B1[2][2];
;     const char* cA = (const char*)g.A + (size_t)cur.pm * tstepA; const char* cB = (const char*)g.Bt + (size_t)cur.pn * tstepB;
;     PG8_STAGE(PG8_SB(0, 0), cB, voffB); PG8_STAGE(PG8_SB(0, 1), cB + hstepB, voffB); PG8_STAGE(PG8_SA(0, 0), cA, voffA); PG8_STAGE(PG8_SA(0, 1), cA + hstepA, voffA);
;     if (wr == 1) PG8_BAR;
;     PG8_WAIT_V(2); PG8_BAR;
;     PG8_STAGE(PG8_SB(1, 0), cB + kstep, voffB); PG8_STAGE(PG8_SA(1, 0), cA + kstep, voffA); PG8_STAGE(PG8_SB(1, 1), cB + hstepB + kstep, voffB);
;     PG8_WAIT_V(6); PG8_BAR;
.LBB0_661:
	v_readlane_b32 s26, v254, 37
	s_lshl_b32 s6, s6, 5
	v_mov_b32_e32 v135, v1
	v_readlane_b32 s27, v254, 38
	s_and_b32 s10, s6, 0x60
	s_add_i32 m0, s30, 0x18000
	v_lshl_add_u64 v[2:3], v[2:3], 0, s[54:55]
	s_waitcnt vmcnt(0)
	v_lshl_add_u64 v[14:15], s[26:27], 0, v[134:135]
	v_mov_b32_e32 v133, v1
	s_lshl_b32 s8, s5, 13
	s_lshl_b32 s9, s10, 7
	s_waitcnt vmcnt(2)
	s_barrier
	global_load_lds_dwordx4 v[2:3], off
	v_lshl_add_u64 v[2:3], v[4:5], 0, s[54:55]
	s_add_i32 m0, s30, 0x1a000
	s_add_i32 s42, s30, 0x8000
	s_add_i32 s43, s30, 0xa000
	v_lshl_add_u64 v[16:17], s[26:27], 0, v[132:133]
	global_load_lds_dwordx4 v[2:3], off
	v_lshl_add_u64 v[2:3], v[14:15], 0, s[54:55]
	s_mov_b32 m0, s42
	s_add_u32 s6, s36, 0x40080
	global_load_lds_dwordx4 v[2:3], off
	v_lshl_add_u64 v[2:3], v[16:17], 0, s[54:55]
	s_mov_b32 m0, s43
	s_addc_u32 s7, s37, 0
	global_load_lds_dwordx4 v[2:3], off
	s_add_i32 m0, s30, 0x1c000
	v_lshl_add_u64 v[2:3], s[6:7], 0, v[0:1]
	global_load_lds_dwordx4 v[2:3], off
	v_lshl_add_u64 v[2:3], s[6:7], 0, v[130:131]
	s_add_i32 m0, s30, 0x1e000
	v_and_b32_e32 v143, 15, v6
	global_load_lds_dwordx4 v[2:3], off
	v_bfe_u32 v3, v6, 4, 2
	v_lshlrev_b32_e32 v4, 4, v3
	v_lshlrev_b32_e32 v5, 2, v6
	v_lshrrev_b32_e32 v2, 4, v6
	v_lshl_or_b32 v4, v143, 6, v4
	v_and_b32_e32 v5, 32, v5
	v_bitop3_b32 v6, v4, s8, v5 bitop3:0xde
	v_bitop3_b32 v147, s9, v4, v5 bitop3:0xf6
	s_cmpk_lt_u32 s4, 0x100
	v_lshlrev_b32_e32 v4, 5, v3
	v_lshlrev_b32_e32 v2, 6, v2
	s_movk_i32 s4, 0xa0
	v_bitop3_b32 v151, v2, s4, v4 bitop3:0xc8
	v_lshlrev_b32_e32 v2, 14, v11
	v_and_b32_e32 v2, 0xffff8000, v2
	v_lshl_or_b32 v153, v3, 3, s10
	v_lshl_add_u32 v2, v10, 11, v2
	v_and_b32_e32 v3, 1, v11
	v_lshl_or_b32 v2, v3, 6, v2
	v_lshl_add_u32 v136, v12, 1, v2
	v_lshlrev_b32_e32 v2, 14, v7
	v_and_b32_e32 v2, 0xffff8000, v2
	s_waitcnt vmcnt(6)
	v_lshl_add_u32 v2, v8, 11, v2
	v_and_b32_e32 v3, 1, v7
	v_lshl_or_b32 v145, s5, 6, v143
	v_lshl_or_b32 v2, v3, 6, v2
	v_readlane_b32 s4, v253, 43
	s_cselect_b64 s[8:9], -1, 0
	s_ashr_i32 s45, s14, 31
	v_mov_b32_e32 v137, v1
	v_lshl_add_u32 v138, v9, 1, v2
	v_mov_b32_e32 v139, v1
	s_mov_b32 s46, 0
	v_add_u32_e32 v155, 0, v6
	v_readlane_b32 s48, v253, 20
	s_mov_b32 s49, s4
	s_mov_b64 s[6:7], s[26:27]
	s_barrier
	v_readlane_b32 s5, v253, 44
	v_lshrrev_b32_e32 v2, 8, v240
	v_bfe_u32 v3, v240, 6, 2
	v_bfe_u32 v4, v240, 5, 1
	v_bfe_u32 v5, v240, 1, 4
	v_lshlrev_b32_e32 v252, 6, v2
	v_lshrrev_b32_e32 v251, 1, v3
	v_lshl_add_u32 v252, v251, 7, v252
	v_and_b32_e32 v251, 1, v3
	v_lshl_add_u32 v252, v251, 5, v252
	v_lshl_add_u32 v252, v4, 4, v252
	v_add_u32_e32 v252, v252, v5
	v_and_b32_e32 v251, 1, v240
	v_lshlrev_b32_e32 v252, 6, v252
	v_lshl_add_u32 v252, v251, 5, v252
	v_lshl_add_u32 v251, v3, 1, v4
	v_lshlrev_b32_e32 v251, 2, v251
	v_lshl_add_u32 v251, v5, 5, v251
	v_lshl_add_u32 v251, v2, 11, v251
	v_add_u32_e32 v251, 0x20000, v251
	s_branch .LBB0_664

; DI float rss_sum(const float* rss, int row) {
;     const f32x4* p = (const f32x4*)(rss + (size_t)row * 16); const f32x4 a = p[0], b = p[1], c = p[2], d = p[3];
;     return (((a.x + a.y) + (a.z + a.w)) + ((b.x + b.y) + (b.z + b.w))) + (((c.x + c.y) + (c.z + c.w)) + ((d.x + d.y) + (d.z + d.w))); }
; DI void row_rstd8(const float* rss, int row0, int lane, int fq, float (&rs)[8]) {
;     float v[2];
; #pragma unroll
;     for (int e = 0; e < 2; ++e) { const int p = 2 * fq + e; const int row = row0 + (p >> 2) * 128 + (p & 3) * 16; v[e] = 1.0f / sqrtf(rss_sum(rss, row) * (1.0f / DM) + EPS); }
; template <class Epi>
; DI void gemm_phase(LAS unsigned char* lds, const int tid, const Gemm g, const StaticOrder& S, const Epi& E) {
;     ...
;     for (;;) {
;         const bool has_next = S.next(ui + 1, nxt);
;         const char* nA = has_next ? (const char*)g.A + (size_t)nxt.pm * tstepA : cA; const char* nB = has_next ? (const char*)g.Bt + (size_t)nxt.pn * tstepB : cB;
;         for (int t = 0; t < nt; t += 2) {
;             const bool last = (t == nt - 2);
;             const char* a1 = cA + (size_t)(t + 1) * kstep;
;             const char* a2 = last ? nA : cA + (size_t)(t + 2) * kstep; const char* b2 = last ? nB : cB + (size_t)(t + 2) * kstep;
;             const char* a3 = a2 + kstep; const char* b3 = b2 + kstep;
.LBB0_666:
	v_readlane_b32 s100, v253, 49
	s_lshl_b32 s101, s49, 14
	s_nop 1
	s_add_u32 s100, s100, s101
	v_readlane_b32 s101, v253, 50
	s_nop 1
	s_addc_u32 s101, s101, 0
	s_nop 4
	global_load_dwordx4 v[228:231], v252, s[100:101]
	global_load_dwordx2 v[232:233], v252, s[100:101] offset:16
	global_load_dwordx2 v[238:239], v252, s[100:101] offset:24
	s_ashr_i32 s13, s12, 31
	s_lshl_b64 s[26:27], s[12:13], 19
	v_readlane_b32 s34, v254, 35
	v_readlane_b32 s35, v254, 36
	s_add_u32 s26, s34, s26
	s_addc_u32 s27, s35, s27
	s_and_b64 s[34:35], s[4:5], exec
	s_cselect_b32 s13, s27, s7
	s_cselect_b32 s52, s26, s6
	s_ashr_i32 s11, s10, 31
	s_lshl_b64 s[34:35], s[10:11], 19
	s_add_u32 s34, s15, s34
	s_addc_u32 s35, s24, s35
	s_and_b64 s[40:41], s[4:5], exec
	s_cselect_b32 s11, s35, s37
	s_cselect_b32 s53, s34, s36
	s_add_u32 s6, s6, 0x40080
	s_addc_u32 s7, s7, 0
	s_add_u32 s56, s36, 0x100
	v_mov_b32_e32 v2, 0
	s_addc_u32 s57, s37, 0
	s_mov_b32 s58, -2
	v_mov_b32_e32 v3, v2
	v_mov_b32_e32 v4, v2
	v_mov_b32_e32 v5, v2
	v_mov_b32_e32 v10, v2
	v_mov_b32_e32 v11, v2
	v_mov_b32_e32 v12, v2
	v_mov_b32_e32 v13, v2
	v_mov_b32_e32 v18, v2
	v_mov_b32_e32 v19, v2
	v_mov_b32_e32 v20, v2
	v_mov_b32_e32 v21, v2
	v_mov_b32_e32 v26, v2
	v_mov_b32_e32 v27, v2
	v_mov_b32_e32 v28, v2
	v_mov_b32_e32 v29, v2
	v_mov_b32_e32 v34, v2
	v_mov_b32_e32 v35, v2
	v_mov_b32_e32 v36, v2
	v_mov_b32_e32 v37, v2
	v_mov_b32_e32 v42, v2
	v_mov_b32_e32 v43, v2
	v_mov_b32_e32 v44, v2
	v_mov_b32_e32 v45, v2
	v_mov_b32_e32 v50, v2
	v_mov_b32_e32 v51, v2
	v_mov_b32_e32 v52, v2
	v_mov_b32_e32 v53, v2
	v_mov_b32_e32 v58, v2
	v_mov_b32_e32 v59, v2
	v_mov_b32_e32 v60, v2
	v_mov_b32_e32 v61, v2
	v_mov_b32_e32 v6, v2
	v_mov_b32_e32 v7, v2
	v_mov_b32_e32 v8, v2
	v_mov_b32_e32 v9, v2
	v_mov_b32_e32 v14, v2
	v_mov_b32_e32 v15, v2
	v_mov_b32_e32 v16, v2
	v_mov_b32_e32 v17, v2
	v_mov_b32_e32 v22, v2
	v_mov_b32_e32 v23, v2
	v_mov_b32_e32 v24, v2
	v_mov_b32_e32 v25, v2
	v_mov_b32_e32 v30, v2
	v_mov_b32_e32 v31, v2
	v_mov_b32_e32 v32, v2
	v_mov_b32_e32 v33, v2
	v_mov_b32_e32 v38, v2
	v_mov_b32_e32 v39, v2
	v_mov_b32_e32 v40, v2
	v_mov_b32_e32 v41, v2
	v_mov_b32_e32 v46, v2
	v_mov_b32_e32 v47, v2
	v_mov_b32_e32 v48, v2
	v_mov_b32_e32 v49, v2
	v_mov_b32_e32 v54, v2
	v_mov_b32_e32 v55, v2
	v_mov_b32_e32 v56, v2
	v_mov_b32_e32 v57, v2
	v_mov_b32_e32 v62, v2
	v_mov_b32_e32 v63, v2
	v_mov_b32_e32 v64, v2
	v_mov_b32_e32 v65, v2
	v_mov_b32_e32 v66, v2
	v_mov_b32_e32 v67, v2
	v_mov_b32_e32 v68, v2
	v_mov_b32_e32 v69, v2
	v_mov_b32_e32 v74, v2
	v_mov_b32_e32 v75, v2
	v_mov_b32_e32 v76, v2
	v_mov_b32_e32 v77, v2
	v_mov_b32_e32 v82, v2
	v_mov_b32_e32 v83, v2
	v_mov_b32_e32 v84, v2
	v_mov_b32_e32 v85, v2
	v_mov_b32_e32 v90, v2
	v_mov_b32_e32 v91, v2
	v_mov_b32_e32 v92, v2
	v_mov_b32_e32 v93, v2
	v_mov_b32_e32 v98, v2
	v_mov_b32_e32 v99, v2
	v_mov_b32_e32 v100, v2
	v_mov_b32_e32 v101, v2
	v_mov_b32_e32 v106, v2
	v_mov_b32_e32 v107, v2
	v_mov_b32_e32 v108, v2
	v_mov_b32_e32 v109, v2
	v_mov_b32_e32 v114, v2
	v_mov_b32_e32 v115, v2
	v_mov_b32_e32 v116, v2
	v_mov_b32_e32 v117, v2
	v_mov_b32_e32 v122, v2
	v_mov_b32_e32 v123, v2
	v_mov_b32_e32 v124, v2
	v_mov_b32_e32 v125, v2
	v_mov_b32_e32 v70, v2
	v_mov_b32_e32 v71, v2
	v_mov_b32_e32 v72, v2
	v_mov_b32_e32 v73, v2
	v_mov_b32_e32 v78, v2
	v_mov_b32_e32 v79, v2
	v_mov_b32_e32 v80, v2
	v_mov_b32_e32 v81, v2
	v_mov_b32_e32 v86, v2
	v_mov_b32_e32 v87, v2
	v_mov_b32_e32 v88, v2
	v_mov_b32_e32 v89, v2
	v_mov_b32_e32 v94, v2
	v_mov_b32_e32 v95, v2
	v_mov_b32_e32 v96, v2
	v_mov_b32_e32 v97, v2
	v_mov_b32_e32 v102, v2
	v_mov_b32_e32 v103, v2
	v_mov_b32_e32 v104, v2
	v_mov_b32_e32 v105, v2
	v_mov_b32_e32 v110, v2
	v_mov_b32_e32 v111, v2
	v_mov_b32_e32 v112, v2
	v_mov_b32_e32 v113, v2
	v_mov_b32_e32 v118, v2
	v_mov_b32_e32 v119, v2
	v_mov_b32_e32 v120, v2
	v_mov_b32_e32 v121, v2
	v_mov_b32_e32 v126, v2
	v_mov_b32_e32 v127, v2
	v_mov_b32_e32 v128, v2
	v_mov_b32_e32 v129, v2
.LBB0_667:
	s_cmp_eq_u32 s58, 2
	s_cbranch_scc0 .Lgu_rs_skip
	s_waitcnt vmcnt(8)
	v_add_f32_e32 v156, v228, v229
	v_add_f32_e32 v157, v230, v231
	v_add_f32_e32 v158, v232, v233
	v_add_f32_e32 v159, v238, v239
	v_add_f32_e32 v156, v156, v157
	v_add_f32_e32 v158, v158, v159
	v_add_f32_e32 v156, v156, v158
	s_nop 1
	v_mov_b32_dpp v157, v156 quad_perm:[1,0,3,2] row_mask:0xf bank_mask:0xf
	s_nop 0
	v_add_f32_e32 v156, v156, v157
	v_fmamk_f32 v156, v156, 0x3a800000, v241
	v_cmp_gt_f32_e32 vcc, s3, v156
	v_mul_f32_e32 v157, 0x4f800000, v156
	s_nop 1
	v_cndmask_b32_e32 v156, v156, v157, vcc
	v_sqrt_f32_e32 v157, v156
	s_nop 0
	v_add_u32_e32 v158, -1, v157
	v_fma_f32 v159, -v158, v157, v156
	v_cmp_ge_f32_e64 s[100:101], 0, v159
	v_add_u32_e32 v159, 1, v157
	s_nop 1
	v_cndmask_b32_e64 v158, v157, v158, s[100:101]
	v_fma_f32 v157, -v159, v157, v156
	v_cmp_lt_f32_e64 s[100:101], 0, v157
	s_nop 1
	v_cndmask_b32_e64 v157, v158, v159, s[100:101]
	v_mul_f32_e32 v158, 0x37800000, v157
	v_cndmask_b32_e32 v157, v157, v158, vcc
	v_cmp_class_f32_e32 vcc, v156, v242
	s_nop 1
	v_cndmask_b32_e32 v156, v157, v156, vcc
	v_div_scale_f32 v157, s[100:101], v156, v156, 1.0
	v_rcp_f32_e32 v158, v157
	s_nop 0
	v_fma_f32 v159, -v157, v158, 1.0
	v_fmac_f32_e32 v158, v159, v158
	v_div_scale_f32 v159, vcc, 1.0, v156, 1.0
	v_mul_f32_e32 v160, v159, v158
	v_fma_f32 v161, -v157, v160, v159
	v_fmac_f32_e32 v160, v161, v158
	v_fma_f32 v157, -v157, v160, v159
	s_nop 0
	v_div_fmas_f32 v157, v157, v158, v160
	v_div_fixup_f32 v156, v157, v156, 1.0
	ds_write_b32 v251, v156

; DI unsigned cvtpk(float lo, float hi) { f32x2_t v = {lo, hi}; bf16x2_t b = __builtin_convertvector(v, bf16x2_t); return __builtin_bit_cast(unsigned, b); }
; DI float fexp2(float x) { return __builtin_amdgcn_exp2f(x); }
; DI float frcp(float x) { return __builtin_amdgcn_rcpf(x); }
;     DI void operator()(const f32x4 (&acc)[2][2][4][2], const Unit& u, int wr, int wc, int fr, int fq) const {
;         const int row0 = u.pm * BM + wr * 64 + fr, col = u.pn * 128 + wc * 32 + 8 * fq;
;         float rs8[8]; row_rstd8(rss, row0, fr + 16 * fq, fq, rs8);
; #pragma unroll
;         for (int ai = 0; ai < 2; ++ai)
; #pragma unroll
;             for (int m = 0; m < 4; ++m) {
;                 const int row = row0 + ai * HALF + m * 16;
;                 const float rstd = rs8[ai * 4 + m];
;                 float hv[8];
; #pragma unroll
;                 for (int n = 0; n < 2; ++n)
; #pragma unroll
;                     for (int j = 0; j < 4; j += 2) {
;                         const float g0 = acc[ai][0][m][n][j] * rstd, u0 = acc[ai][1][m][n][j] * rstd, g1 = acc[ai][0][m][n][j + 1] * rstd, u1 = acc[ai][1][m][n][j + 1] * rstd;
;                         const float d0 = 1.0f + fexp2(fminf(-g0 * LOG2E, 60.0f)), d1 = 1.0f + fexp2(fminf(-g1 * LOG2E, 60.0f));
;                         const float rp = frcp(d0 * d1);
;                         hv[4 * n + j] = g0 * (d1 * rp) * u0; hv[4 * n + j + 1] = g1 * (d0 * rp) * u1;
;                     }
;                 u32x4 w; w.x = cvtpk(hv[0], hv[1]); w.y = cvtpk(hv[2], hv[3]); w.z = cvtpk(hv[4], hv[5]); w.w = cvtpk(hv[6], hv[7]);
;                 *(u32x4*)(H + (size_t)row * FF + col) = w;
.LBB0_670:
	v_lshl_add_u32 v156, s49, 8, v145
	v_lshl_or_b32 v148, s48, 7, v153
	v_lshlrev_b32_e32 v149, 5, v145
	v_add_u32_e32 v149, 0x20000, v149
	ds_read_b32 v158, v149
	ds_read_b32 v152, v149 offset:8
	ds_read_b32 v146, v149 offset:16
	ds_read_b32 v142, v149 offset:24
	ds_read_b32 v154, v149 offset:4
	s_waitcnt lgkmcnt(4)
	v_pk_mul_f32 v[126:127], v[126:127], v[158:159] op_sel_hi:[1,0]
	v_pk_mul_f32 v[122:123], v[122:123], v[158:159] op_sel_hi:[1,0]
	v_mul_f32_e32 v141, 0xbfb8aa3b, v126
	v_min_f32_e32 v141, 0x42700000, v141
	v_exp_f32_e32 v161, v141
	v_mul_f32_e32 v141, 0xbfb8aa3b, v127
	v_min_f32_e32 v141, 0x42700000, v141
	v_exp_f32_e32 v160, v141
	v_pk_mul_f32 v[124:125], v[124:125], v[158:159] op_sel_hi:[1,0]
	v_pk_mul_f32 v[118:119], v[118:119], v[158:159] op_sel_hi:[1,0]
	v_pk_mul_f32 v[114:115], v[114:115], v[158:159] op_sel_hi:[1,0]
	v_pk_add_f32 v[160:161], v[160:161], 1.0 op_sel_hi:[1,0]
	v_pk_mul_f32 v[116:117], v[116:117], v[158:159] op_sel_hi:[1,0]
	v_mul_f32_e32 v141, v161, v160
	v_rcp_f32_e32 v162, v141
	ds_read_b32 v150, v149 offset:12
	ds_read_b32 v144, v149 offset:20
	ds_read_b32 v140, v149 offset:28
	v_pk_mul_f32 v[160:161], v[160:161], v[162:163] op_sel_hi:[1,0]
	v_ashrrev_i32_e32 v149, 31, v148
	v_pk_mul_f32 v[126:127], v[126:127], v[160:161]
	s_waitcnt lgkmcnt(3)
	v_pk_mul_f32 v[110:111], v[110:111], v[154:155] op_sel_hi:[1,0]
	v_pk_mul_f32 v[122:123], v[122:123], v[126:127]
	v_pk_mul_f32 v[126:127], v[128:129], v[158:159] op_sel_hi:[1,0]
	v_pk_mul_f32 v[106:107], v[106:107], v[154:155] op_sel_hi:[1,0]
	v_mul_f32_e32 v128, 0xbfb8aa3b, v126
	v_min_f32_e32 v128, 0x42700000, v128
	v_exp_f32_e32 v129, v128
	v_mul_f32_e32 v128, 0xbfb8aa3b, v127
	v_min_f32_e32 v128, 0x42700000, v128
	v_exp_f32_e32 v128, v128
	v_pk_mul_f32 v[108:109], v[108:109], v[154:155] op_sel_hi:[1,0]
	v_pk_mul_f32 v[102:103], v[102:103], v[154:155] op_sel_hi:[1,0]
	v_pk_mul_f32 v[98:99], v[98:99], v[154:155] op_sel_hi:[1,0]
	v_pk_add_f32 v[128:129], v[128:129], 1.0 op_sel_hi:[1,0]
	v_pk_mul_f32 v[100:101], v[100:101], v[154:155] op_sel_hi:[1,0]
	v_mul_f32_e32 v141, v129, v128
	v_rcp_f32_e32 v160, v141
	v_pk_mul_f32 v[94:95], v[94:95], v[152:153] op_sel_hi:[1,0]
	v_pk_mul_f32 v[90:91], v[90:91], v[152:153] op_sel_hi:[1,0]
	v_pk_mul_f32 v[92:93], v[92:93], v[152:153] op_sel_hi:[1,0]
	v_pk_mul_f32 v[128:129], v[128:129], v[160:161] op_sel_hi:[1,0]
	v_pk_mul_f32 v[86:87], v[86:87], v[152:153] op_sel_hi:[1,0]
	v_pk_mul_f32 v[126:127], v[126:127], v[128:129]
	v_pk_mul_f32 v[82:83], v[82:83], v[152:153] op_sel_hi:[1,0]
	v_pk_mul_f32 v[124:125], v[124:125], v[126:127]
	v_mul_f32_e32 v126, 0xbfb8aa3b, v118
	v_min_f32_e32 v126, 0x42700000, v126
	v_exp_f32_e32 v127, v126
	v_mul_f32_e32 v126, 0xbfb8aa3b, v119
	v_min_f32_e32 v126, 0x42700000, v126
	v_exp_f32_e32 v126, v126
	v_pk_mul_f32 v[84:85], v[84:85], v[152:153] op_sel_hi:[1,0]
	s_waitcnt lgkmcnt(2)
	v_pk_mul_f32 v[78:79], v[78:79], v[150:151] op_sel_hi:[1,0]
	v_pk_mul_f32 v[74:75], v[74:75], v[150:151] op_sel_hi:[1,0]
	v_pk_add_f32 v[126:127], v[126:127], 1.0 op_sel_hi:[1,0]
	v_pk_mul_f32 v[76:77], v[76:77], v[150:151] op_sel_hi:[1,0]
	v_mul_f32_e32 v128, v127, v126
	v_rcp_f32_e32 v128, v128
	v_pk_mul_f32 v[70:71], v[70:71], v[150:151] op_sel_hi:[1,0]
	v_pk_mul_f32 v[66:67], v[66:67], v[150:151] op_sel_hi:[1,0]
	v_pk_mul_f32 v[68:69], v[68:69], v[150:151] op_sel_hi:[1,0]
	v_pk_mul_f32 v[126:127], v[126:127], v[128:129] op_sel_hi:[1,0]
	v_pk_mul_f32 v[62:63], v[62:63], v[146:147] op_sel_hi:[1,0]
	v_pk_mul_f32 v[118:119], v[118:119], v[126:127]
	v_pk_mul_f32 v[58:59], v[58:59], v[146:147] op_sel_hi:[1,0]
	v_pk_mul_f32 v[114:115], v[114:115], v[118:119]
	v_pk_mul_f32 v[118:119], v[120:121], v[158:159] op_sel_hi:[1,0]
	v_pk_mul_f32 v[60:61], v[60:61], v[146:147] op_sel_hi:[1,0]
	v_mul_f32_e32 v120, 0xbfb8aa3b, v118
	v_min_f32_e32 v120, 0x42700000, v120
	v_exp_f32_e32 v121, v120
	v_mul_f32_e32 v120, 0xbfb8aa3b, v119
	v_min_f32_e32 v120, 0x42700000, v120
	v_exp_f32_e32 v120, v120
	v_pk_mul_f32 v[54:55], v[54:55], v[146:147] op_sel_hi:[1,0]
	v_pk_mul_f32 v[50:51], v[50:51], v[146:147] op_sel_hi:[1,0]
	v_pk_mul_f32 v[52:53], v[52:53], v[146:147] op_sel_hi:[1,0]
	v_pk_add_f32 v[120:121], v[120:121], 1.0 op_sel_hi:[1,0]
	s_waitcnt lgkmcnt(1)
	v_pk_mul_f32 v[46:47], v[46:47], v[144:145] op_sel_hi:[1,0]
	v_mul_f32_e32 v126, v121, v120
	v_rcp_f32_e32 v126, v126
	v_pk_mul_f32 v[42:43], v[42:43], v[144:145] op_sel_hi:[1,0]
	v_pk_mul_f32 v[44:45], v[44:45], v[144:145] op_sel_hi:[1,0]
	v_pk_mul_f32 v[38:39], v[38:39], v[144:145] op_sel_hi:[1,0]
	v_pk_mul_f32 v[120:121], v[120:121], v[126:127] op_sel_hi:[1,0]
	v_pk_mul_f32 v[34:35], v[34:35], v[144:145] op_sel_hi:[1,0]
	v_pk_mul_f32 v[118:119], v[118:119], v[120:121]
	v_cvt_pk_bf16_f32 v120, v114, v115
	v_pk_mul_f32 v[116:117], v[116:117], v[118:119]
	v_mov_b64_e32 v[114:115], s[74:75]
	v_cvt_pk_bf16_f32 v118, v122, v123
	v_cvt_pk_bf16_f32 v121, v116, v117
	v_mad_i64_i32 v[122:123], s[6:7], v156, s77, v[114:115]
	v_lshlrev_b64 v[116:117], 1, v[148:149]
	v_cvt_pk_bf16_f32 v119, v124, v125
	v_lshl_add_u64 v[122:123], v[122:123], 0, v[116:117]
	global_store_dwordx4 v[122:123], v[118:121], off
	v_pk_mul_f32 v[36:37], v[36:37], v[144:145] op_sel_hi:[1,0]
	v_pk_mul_f32 v[30:31], v[30:31], v[142:143] op_sel_hi:[1,0]
	v_mul_f32_e32 v118, 0xbfb8aa3b, v110
	v_min_f32_e32 v118, 0x42700000, v118
	v_exp_f32_e32 v119, v118
	v_mul_f32_e32 v118, 0xbfb8aa3b, v111
	v_min_f32_e32 v118, 0x42700000, v118
	v_exp_f32_e32 v118, v118
	v_pk_mul_f32 v[26:27], v[26:27], v[142:143] op_sel_hi:[1,0]
	v_pk_mul_f32 v[28:29], v[28:29], v[142:143] op_sel_hi:[1,0]
	v_pk_mul_f32 v[22:23], v[22:23], v[142:143] op_sel_hi:[1,0]
	v_pk_add_f32 v[118:119], v[118:119], 1.0 op_sel_hi:[1,0]
	v_pk_mul_f32 v[18:19], v[18:19], v[142:143] op_sel_hi:[1,0]
	v_mul_f32_e32 v120, v119, v118
	v_rcp_f32_e32 v120, v120
	v_pk_mul_f32 v[20:21], v[20:21], v[142:143] op_sel_hi:[1,0]
	s_waitcnt lgkmcnt(0)
; DI unsigned cvtpk(float lo, float hi) { f32x2_t v = {lo, hi}; bf16x2_t b = __builtin_convertvector(v, bf16x2_t); return __builtin_bit_cast(unsigned, b); }
; DI float fexp2(float x) { return __builtin_amdgcn_exp2f(x); }
; DI float frcp(float x) { return __builtin_amdgcn_rcpf(x); }
;     DI void operator()(const f32x4 (&acc)[2][2][4][2], const Unit& u, int wr, int wc, int fr, int fq) const {
;     ...
;             for (int m = 0; m < 4; ++m) {
;                 const int row = row0 + ai * HALF + m * 16;
;                 const float rstd = rs8[ai * 4 + m];
;                 float hv[8];
; #pragma unroll
;                 for (int n = 0; n < 2; ++n)
; #pragma unroll
;                     for (int j = 0; j < 4; j += 2) {
;                         const float g0 = acc[ai][0][m][n][j] * rstd, u0 = acc[ai][1][m][n][j] * rstd, g1 = acc[ai][0][m][n][j + 1] * rstd, u1 = acc[ai][1][m][n][j + 1] * rstd;
;                         const float d0 = 1.0f + fexp2(fminf(-g0 * LOG2E, 60.0f)), d1 = 1.0f + fexp2(fminf(-g1 * LOG2E, 60.0f));
;                         const float rp = frcp(d0 * d1);
;                         hv[4 * n + j] = g0 * (d1 * rp) * u0; hv[4 * n + j + 1] = g1 * (d0 * rp) * u1;
;                     }
;                 u32x4 w; w.x = cvtpk(hv[0], hv[1]); w.y = cvtpk(hv[2], hv[3]); w.z = cvtpk(hv[4], hv[5]); w.w = cvtpk(hv[6], hv[7]);
;                 *(u32x4*)(H + (size_t)row * FF + col) = w;
;             }
	v_pk_mul_f32 v[14:15], v[14:15], v[140:141] op_sel_hi:[1,0]
	v_pk_mul_f32 v[10:11], v[10:11], v[140:141] op_sel_hi:[1,0]
	v_pk_mul_f32 v[118:119], v[118:119], v[120:121] op_sel_hi:[1,0]
	v_pk_mul_f32 v[12:13], v[12:13], v[140:141] op_sel_hi:[1,0]
	v_pk_mul_f32 v[110:111], v[110:111], v[118:119]
	v_pk_mul_f32 v[6:7], v[6:7], v[140:141] op_sel_hi:[1,0]
	v_pk_mul_f32 v[106:107], v[106:107], v[110:111]
	v_pk_mul_f32 v[110:111], v[112:113], v[154:155] op_sel_hi:[1,0]
	v_pk_mul_f32 v[2:3], v[2:3], v[140:141] op_sel_hi:[1,0]
	v_mul_f32_e32 v112, 0xbfb8aa3b, v110
	v_min_f32_e32 v112, 0x42700000, v112
	v_exp_f32_e32 v113, v112
	v_mul_f32_e32 v112, 0xbfb8aa3b, v111
	v_min_f32_e32 v112, 0x42700000, v112
	v_exp_f32_e32 v112, v112
	v_pk_mul_f32 v[4:5], v[4:5], v[140:141] op_sel_hi:[1,0]
	s_andn2_b64 vcc, exec, s[4:5]
	v_pk_add_f32 v[112:113], v[112:113], 1.0 op_sel_hi:[1,0]
	s_nop 0
	v_mul_f32_e32 v118, v113, v112
	v_rcp_f32_e32 v118, v118
	s_nop 0
	v_pk_mul_f32 v[112:113], v[112:113], v[118:119] op_sel_hi:[1,0]
	s_nop 0
	v_pk_mul_f32 v[110:111], v[110:111], v[112:113]
	s_nop 0
	v_pk_mul_f32 v[108:109], v[108:109], v[110:111]
	v_mul_f32_e32 v110, 0xbfb8aa3b, v102
	v_min_f32_e32 v110, 0x42700000, v110
	v_exp_f32_e32 v111, v110
	v_mul_f32_e32 v110, 0xbfb8aa3b, v103
	v_min_f32_e32 v110, 0x42700000, v110
	v_exp_f32_e32 v110, v110
	s_nop 0
	v_pk_add_f32 v[110:111], v[110:111], 1.0 op_sel_hi:[1,0]
	s_nop 0
	v_mul_f32_e32 v112, v111, v110
	v_rcp_f32_e32 v112, v112
	s_nop 0
	v_pk_mul_f32 v[110:111], v[110:111], v[112:113] op_sel_hi:[1,0]
	s_nop 0
	v_pk_mul_f32 v[102:103], v[102:103], v[110:111]
	s_nop 0
	v_pk_mul_f32 v[102:103], v[98:99], v[102:103]
	v_pk_mul_f32 v[98:99], v[104:105], v[154:155] op_sel_hi:[1,0]
	s_nop 0
	v_mul_f32_e32 v104, 0xbfb8aa3b, v98
	v_min_f32_e32 v104, 0x42700000, v104
	v_exp_f32_e32 v105, v104
	v_mul_f32_e32 v104, 0xbfb8aa3b, v99
	v_min_f32_e32 v104, 0x42700000, v104
	v_exp_f32_e32 v104, v104
	s_nop 0
	v_pk_add_f32 v[104:105], v[104:105], 1.0 op_sel_hi:[1,0]
	s_nop 0
	v_mul_f32_e32 v110, v105, v104
	v_rcp_f32_e32 v110, v110
	s_nop 0
	v_pk_mul_f32 v[104:105], v[104:105], v[110:111] op_sel_hi:[1,0]
	s_nop 0
	v_pk_mul_f32 v[98:99], v[98:99], v[104:105]
	v_or_b32_e32 v110, 16, v156
	v_pk_mul_f32 v[104:105], v[100:101], v[98:99]
	v_cvt_pk_bf16_f32 v100, v102, v103
	v_mad_i64_i32 v[102:103], s[6:7], v110, s77, v[114:115]
	v_cvt_pk_bf16_f32 v98, v106, v107
	v_cvt_pk_bf16_f32 v99, v108, v109
	v_cvt_pk_bf16_f32 v101, v104, v105
	v_lshl_add_u64 v[102:103], v[102:103], 0, v[116:117]
	global_store_dwordx4 v[102:103], v[98:101], off
	s_nop 1
	v_mul_f32_e32 v98, 0xbfb8aa3b, v94
	v_min_f32_e32 v98, 0x42700000, v98
	v_exp_f32_e32 v99, v98
	v_mul_f32_e32 v98, 0xbfb8aa3b, v95
	v_min_f32_e32 v98, 0x42700000, v98
	v_exp_f32_e32 v98, v98
	s_nop 0
	v_pk_add_f32 v[98:99], v[98:99], 1.0 op_sel_hi:[1,0]
	s_nop 0
	v_mul_f32_e32 v100, v99, v98
	v_rcp_f32_e32 v100, v100
	s_nop 0
	v_pk_mul_f32 v[98:99], v[98:99], v[100:101] op_sel_hi:[1,0]
	s_nop 0
	v_pk_mul_f32 v[94:95], v[94:95], v[98:99]
	s_nop 0
	v_pk_mul_f32 v[90:91], v[90:91], v[94:95]
	v_pk_mul_f32 v[94:95], v[96:97], v[152:153] op_sel_hi:[1,0]
	s_nop 0
	v_mul_f32_e32 v96, 0xbfb8aa3b, v94
	v_min_f32_e32 v96, 0x42700000, v96
	v_exp_f32_e32 v97, v96
	v_mul_f32_e32 v96, 0xbfb8aa3b, v95
	v_min_f32_e32 v96, 0x42700000, v96
	v_exp_f32_e32 v96, v96
	s_nop 0
	v_pk_add_f32 v[96:97], v[96:97], 1.0 op_sel_hi:[1,0]
	s_nop 0
	v_mul_f32_e32 v98, v97, v96
	v_rcp_f32_e32 v98, v98
	s_nop 0
	v_pk_mul_f32 v[96:97], v[96:97], v[98:99] op_sel_hi:[1,0]
	s_nop 0
	v_pk_mul_f32 v[94:95], v[94:95], v[96:97]
	s_nop 0
	v_pk_mul_f32 v[92:93], v[92:93], v[94:95]
	v_mul_f32_e32 v94, 0xbfb8aa3b, v86
	v_min_f32_e32 v94, 0x42700000, v94
	v_exp_f32_e32 v95, v94
	v_mul_f32_e32 v94, 0xbfb8aa3b, v87
	v_min_f32_e32 v94, 0x42700000, v94
	v_exp_f32_e32 v94, v94
	s_nop 0
	v_pk_add_f32 v[94:95], v[94:95], 1.0 op_sel_hi:[1,0]
	s_nop 0
	v_mul_f32_e32 v96, v95, v94
	v_rcp_f32_e32 v96, v96
	s_nop 0
	v_pk_mul_f32 v[94:95], v[94:95], v[96:97] op_sel_hi:[1,0]
	s_nop 0
	v_pk_mul_f32 v[86:87], v[86:87], v[94:95]
	s_nop 0
	v_pk_mul_f32 v[86:87], v[82:83], v[86:87]
	v_pk_mul_f32 v[82:83], v[88:89], v[152:153] op_sel_hi:[1,0]
	s_nop 0
	v_mul_f32_e32 v88, 0xbfb8aa3b, v82
	v_min_f32_e32 v88, 0x42700000, v88
	v_exp_f32_e32 v89, v88
	v_mul_f32_e32 v88, 0xbfb8aa3b, v83
	v_min_f32_e32 v88, 0x42700000, v88
	v_exp_f32_e32 v88, v88
	s_nop 0
	v_pk_add_f32 v[88:89], v[88:89], 1.0 op_sel_hi:[1,0]
	s_nop 0
	v_mul_f32_e32 v94, v89, v88
	v_rcp_f32_e32 v94, v94
	s_nop 0
	v_pk_mul_f32 v[88:89], v[88:89], v[94:95] op_sel_hi:[1,0]
	s_nop 0
	v_pk_mul_f32 v[82:83], v[82:83], v[88:89]
	v_or_b32_e32 v94, 32, v156
	v_pk_mul_f32 v[88:89], v[84:85], v[82:83]
	v_cvt_pk_bf16_f32 v84, v86, v87
	v_mad_i64_i32 v[86:87], s[6:7], v94, s77, v[114:115]
	v_cvt_pk_bf16_f32 v82, v90, v91
	v_cvt_pk_bf16_f32 v83, v92, v93
	v_cvt_pk_bf16_f32 v85, v88, v89
	v_lshl_add_u64 v[86:87], v[86:87], 0, v[116:117]
	global_store_dwordx4 v[86:87], v[82:85], off
	s_nop 1
	v_mul_f32_e32 v82, 0xbfb8aa3b, v78
	v_min_f32_e32 v82, 0x42700000, v82
	v_exp_f32_e32 v83, v82
	v_mul_f32_e32 v82, 0xbfb8aa3b, v79
	v_min_f32_e32 v82, 0x42700000, v82
	v_exp_f32_e32 v82, v82
	s_nop 0
	v_pk_add_f32 v[82:83], v[82:83], 1.0 op_sel_hi:[1,0]
	s_nop 0
	v_mul_f32_e32 v84, v83, v82
	v_rcp_f32_e32 v84, v84
	s_nop 0
	v_pk_mul_f32 v[82:83], v[82:83], v[84:85] op_sel_hi:[1,0]
	s_nop 0
	v_pk_mul_f32 v[78:79], v[78:79], v[82:83]
	s_nop 0
	v_pk_mul_f32 v[74:75], v[74:75], v[78:79]
	v_pk_mul_f32 v[78:79], v[80:81], v[150:151] op_sel_hi:[1,0]
	s_nop 0
	v_mul_f32_e32 v80, 0xbfb8aa3b, v78
	v_min_f32_e32 v80, 0x42700000, v80
	v_exp_f32_e32 v81, v80
; DI unsigned cvtpk(float lo, float hi) { f32x2_t v = {lo, hi}; bf16x2_t b = __builtin_convertvector(v, bf16x2_t); return __builtin_bit_cast(unsigned, b); }
; DI float fexp2(float x) { return __builtin_amdgcn_exp2f(x); }
; DI float frcp(float x) { return __builtin_amdgcn_rcpf(x); }
;     DI void operator()(const f32x4 (&acc)[2][2][4][2], const Unit& u, int wr, int wc, int fr, int fq) const {
;     ...
;             for (int m = 0; m < 4; ++m) {
;                 const int row = row0 + ai * HALF + m * 16;
;                 const float rstd = rs8[ai * 4 + m];
;                 float hv[8];
; #pragma unroll
;                 for (int n = 0; n < 2; ++n)
; #pragma unroll
;                     for (int j = 0; j < 4; j += 2) {
;                         const float g0 = acc[ai][0][m][n][j] * rstd, u0 = acc[ai][1][m][n][j] * rstd, g1 = acc[ai][0][m][n][j + 1] * rstd, u1 = acc[ai][1][m][n][j + 1] * rstd;
;                         const float d0 = 1.0f + fexp2(fminf(-g0 * LOG2E, 60.0f)), d1 = 1.0f + fexp2(fminf(-g1 * LOG2E, 60.0f));
;                         const float rp = frcp(d0 * d1);
;                         hv[4 * n + j] = g0 * (d1 * rp) * u0; hv[4 * n + j + 1] = g1 * (d0 * rp) * u1;
;                     }
;                 u32x4 w; w.x = cvtpk(hv[0], hv[1]); w.y = cvtpk(hv[2], hv[3]); w.z = cvtpk(hv[4], hv[5]); w.w = cvtpk(hv[6], hv[7]);
;                 *(u32x4*)(H + (size_t)row * FF + col) = w;
;             }
	v_mul_f32_e32 v80, 0xbfb8aa3b, v79
	v_min_f32_e32 v80, 0x42700000, v80
	v_exp_f32_e32 v80, v80
	s_nop 0
	v_pk_add_f32 v[80:81], v[80:81], 1.0 op_sel_hi:[1,0]
	s_nop 0
	v_mul_f32_e32 v82, v81, v80
	v_rcp_f32_e32 v82, v82
	s_nop 0
	v_pk_mul_f32 v[80:81], v[80:81], v[82:83] op_sel_hi:[1,0]
	s_nop 0
	v_pk_mul_f32 v[78:79], v[78:79], v[80:81]
	s_nop 0
	v_pk_mul_f32 v[76:77], v[76:77], v[78:79]
	v_mul_f32_e32 v78, 0xbfb8aa3b, v70
	v_min_f32_e32 v78, 0x42700000, v78
	v_exp_f32_e32 v79, v78
	v_mul_f32_e32 v78, 0xbfb8aa3b, v71
	v_min_f32_e32 v78, 0x42700000, v78
	v_exp_f32_e32 v78, v78
	s_nop 0
	v_pk_add_f32 v[78:79], v[78:79], 1.0 op_sel_hi:[1,0]
	s_nop 0
	v_mul_f32_e32 v80, v79, v78
	v_rcp_f32_e32 v80, v80
	s_nop 0
	v_pk_mul_f32 v[78:79], v[78:79], v[80:81] op_sel_hi:[1,0]
	s_nop 0
	v_pk_mul_f32 v[70:71], v[70:71], v[78:79]
	s_nop 0
	v_pk_mul_f32 v[70:71], v[66:67], v[70:71]
	v_pk_mul_f32 v[66:67], v[72:73], v[150:151] op_sel_hi:[1,0]
	s_nop 0
	v_mul_f32_e32 v72, 0xbfb8aa3b, v66
	v_min_f32_e32 v72, 0x42700000, v72
	v_exp_f32_e32 v73, v72
	v_mul_f32_e32 v72, 0xbfb8aa3b, v67
	v_min_f32_e32 v72, 0x42700000, v72
	v_exp_f32_e32 v72, v72
	s_nop 0
	v_pk_add_f32 v[72:73], v[72:73], 1.0 op_sel_hi:[1,0]
	s_nop 0
	v_mul_f32_e32 v78, v73, v72
	v_rcp_f32_e32 v78, v78
	s_nop 0
	v_pk_mul_f32 v[72:73], v[72:73], v[78:79] op_sel_hi:[1,0]
	s_nop 0
	v_pk_mul_f32 v[66:67], v[66:67], v[72:73]
	v_or_b32_e32 v78, 48, v156
	v_pk_mul_f32 v[72:73], v[68:69], v[66:67]
	v_cvt_pk_bf16_f32 v68, v70, v71
	v_mad_i64_i32 v[70:71], s[6:7], v78, s77, v[114:115]
	v_cvt_pk_bf16_f32 v66, v74, v75
	v_cvt_pk_bf16_f32 v67, v76, v77
	v_cvt_pk_bf16_f32 v69, v72, v73
	v_lshl_add_u64 v[70:71], v[70:71], 0, v[116:117]
	global_store_dwordx4 v[70:71], v[66:69], off
	s_nop 1
	v_mul_f32_e32 v66, 0xbfb8aa3b, v62
	v_min_f32_e32 v66, 0x42700000, v66
	v_exp_f32_e32 v67, v66
	v_mul_f32_e32 v66, 0xbfb8aa3b, v63
	v_min_f32_e32 v66, 0x42700000, v66
	v_exp_f32_e32 v66, v66
	v_add_u32_e32 v69, 0x80, v156
	v_pk_add_f32 v[66:67], v[66:67], 1.0 op_sel_hi:[1,0]
	s_nop 0
	v_mul_f32_e32 v68, v67, v66
	v_rcp_f32_e32 v68, v68
	s_nop 0
	v_pk_mul_f32 v[66:67], v[66:67], v[68:69] op_sel_hi:[1,0]
	s_nop 0
	v_pk_mul_f32 v[62:63], v[62:63], v[66:67]
	s_nop 0
	v_pk_mul_f32 v[58:59], v[58:59], v[62:63]
	v_pk_mul_f32 v[62:63], v[64:65], v[146:147] op_sel_hi:[1,0]
	s_nop 0
	v_mul_f32_e32 v64, 0xbfb8aa3b, v62
	v_min_f32_e32 v64, 0x42700000, v64
	v_exp_f32_e32 v65, v64
	v_mul_f32_e32 v64, 0xbfb8aa3b, v63
	v_min_f32_e32 v64, 0x42700000, v64
	v_exp_f32_e32 v64, v64
	s_nop 0
	v_pk_add_f32 v[64:65], v[64:65], 1.0 op_sel_hi:[1,0]
	s_nop 0
	v_mul_f32_e32 v66, v65, v64
	v_rcp_f32_e32 v66, v66
	s_nop 0
	v_pk_mul_f32 v[64:65], v[64:65], v[66:67] op_sel_hi:[1,0]
	s_nop 0
	v_pk_mul_f32 v[62:63], v[62:63], v[64:65]
	s_nop 0
	v_pk_mul_f32 v[60:61], v[60:61], v[62:63]
	v_mul_f32_e32 v62, 0xbfb8aa3b, v54
	v_min_f32_e32 v62, 0x42700000, v62
	v_exp_f32_e32 v63, v62
	v_mul_f32_e32 v62, 0xbfb8aa3b, v55
	v_min_f32_e32 v62, 0x42700000, v62
	v_exp_f32_e32 v62, v62
	s_nop 0
	v_pk_add_f32 v[62:63], v[62:63], 1.0 op_sel_hi:[1,0]
	s_nop 0
	v_mul_f32_e32 v64, v63, v62
	v_rcp_f32_e32 v64, v64
	s_nop 0
	v_pk_mul_f32 v[62:63], v[62:63], v[64:65] op_sel_hi:[1,0]
	s_nop 0
	v_pk_mul_f32 v[54:55], v[54:55], v[62:63]
	s_nop 0
	v_pk_mul_f32 v[54:55], v[50:51], v[54:55]
	v_pk_mul_f32 v[50:51], v[56:57], v[146:147] op_sel_hi:[1,0]
	s_nop 0
	v_mul_f32_e32 v56, 0xbfb8aa3b, v50
	v_min_f32_e32 v56, 0x42700000, v56
	v_exp_f32_e32 v57, v56
	v_mul_f32_e32 v56, 0xbfb8aa3b, v51
	v_min_f32_e32 v56, 0x42700000, v56
	v_exp_f32_e32 v56, v56
	s_nop 0
	v_pk_add_f32 v[56:57], v[56:57], 1.0 op_sel_hi:[1,0]
	s_nop 0
	v_mul_f32_e32 v62, v57, v56
	v_rcp_f32_e32 v62, v62
	s_nop 0
	v_pk_mul_f32 v[56:57], v[56:57], v[62:63] op_sel_hi:[1,0]
	s_nop 0
	v_pk_mul_f32 v[50:51], v[50:51], v[56:57]
	s_nop 0
	v_pk_mul_f32 v[56:57], v[52:53], v[50:51]
	v_cvt_pk_bf16_f32 v52, v54, v55
	v_mad_i64_i32 v[54:55], s[6:7], v69, s77, v[114:115]
	v_cvt_pk_bf16_f32 v50, v58, v59
	v_cvt_pk_bf16_f32 v51, v60, v61
	v_cvt_pk_bf16_f32 v53, v56, v57
	v_lshl_add_u64 v[54:55], v[54:55], 0, v[116:117]
	global_store_dwordx4 v[54:55], v[50:53], off
	s_nop 1
	v_mul_f32_e32 v50, 0xbfb8aa3b, v46
	v_min_f32_e32 v50, 0x42700000, v50
	v_exp_f32_e32 v51, v50
	v_mul_f32_e32 v50, 0xbfb8aa3b, v47
	v_min_f32_e32 v50, 0x42700000, v50
	v_exp_f32_e32 v50, v50
	s_nop 0
	v_pk_add_f32 v[50:51], v[50:51], 1.0 op_sel_hi:[1,0]
	s_nop 0
	v_mul_f32_e32 v52, v51, v50
	v_rcp_f32_e32 v52, v52
	s_nop 0
	v_pk_mul_f32 v[50:51], v[50:51], v[52:53] op_sel_hi:[1,0]
	s_nop 0
	v_pk_mul_f32 v[46:47], v[46:47], v[50:51]
	s_nop 0
	v_pk_mul_f32 v[42:43], v[42:43], v[46:47]
	v_pk_mul_f32 v[46:47], v[48:49], v[144:145] op_sel_hi:[1,0]
	s_nop 0
	v_mul_f32_e32 v48, 0xbfb8aa3b, v46
	v_min_f32_e32 v48, 0x42700000, v48
	v_exp_f32_e32 v49, v48
	v_mul_f32_e32 v48, 0xbfb8aa3b, v47
	v_min_f32_e32 v48, 0x42700000, v48
	v_exp_f32_e32 v48, v48
	s_nop 0
	v_pk_add_f32 v[48:49], v[48:49], 1.0 op_sel_hi:[1,0]
	s_nop 0
	v_mul_f32_e32 v50, v49, v48
	v_rcp_f32_e32 v50, v50
	s_nop 0
	v_pk_mul_f32 v[48:49], v[48:49], v[50:51] op_sel_hi:[1,0]
	s_nop 0
	v_pk_mul_f32 v[46:47], v[46:47], v[48:49]
	s_nop 0
	v_pk_mul_f32 v[44:45], v[44:45], v[46:47]
	v_mul_f32_e32 v46, 0xbfb8aa3b, v38
	v_min_f32_e32 v46, 0x42700000, v46
	v_exp_f32_e32 v47, v46
	v_mul_f32_e32 v46, 0xbfb8aa3b, v39
	v_min_f32_e32 v46, 0x42700000, v46
	v_exp_f32_e32 v46, v46
	s_nop 0
	v_pk_add_f32 v[46:47], v[46:47], 1.0 op_sel_hi:[1,0]
	s_nop 0
	v_mul_f32_e32 v48, v47, v46
	v_rcp_f32_e32 v48, v48
	s_nop 0
	v_pk_mul_f32 v[46:47], v[46:47], v[48:49] op_sel_hi:[1,0]
	s_nop 0
	v_pk_mul_f32 v[38:39], v[38:39], v[46:47]
; DI unsigned cvtpk(float lo, float hi) { f32x2_t v = {lo, hi}; bf16x2_t b = __builtin_convertvector(v, bf16x2_t); return __builtin_bit_cast(unsigned, b); }
; DI float fexp2(float x) { return __builtin_amdgcn_exp2f(x); }
; DI float frcp(float x) { return __builtin_amdgcn_rcpf(x); }
;     DI void operator()(const f32x4 (&acc)[2][2][4][2], const Unit& u, int wr, int wc, int fr, int fq) const {
;     ...
;             for (int m = 0; m < 4; ++m) {
;                 const int row = row0 + ai * HALF + m * 16;
;                 const float rstd = rs8[ai * 4 + m];
;                 float hv[8];
; #pragma unroll
;                 for (int n = 0; n < 2; ++n)
; #pragma unroll
;                     for (int j = 0; j < 4; j += 2) {
;                         const float g0 = acc[ai][0][m][n][j] * rstd, u0 = acc[ai][1][m][n][j] * rstd, g1 = acc[ai][0][m][n][j + 1] * rstd, u1 = acc[ai][1][m][n][j + 1] * rstd;
;                         const float d0 = 1.0f + fexp2(fminf(-g0 * LOG2E, 60.0f)), d1 = 1.0f + fexp2(fminf(-g1 * LOG2E, 60.0f));
;                         const float rp = frcp(d0 * d1);
;                         hv[4 * n + j] = g0 * (d1 * rp) * u0; hv[4 * n + j + 1] = g1 * (d0 * rp) * u1;
;                     }
;                 u32x4 w; w.x = cvtpk(hv[0], hv[1]); w.y = cvtpk(hv[2], hv[3]); w.z = cvtpk(hv[4], hv[5]); w.w = cvtpk(hv[6], hv[7]);
;                 *(u32x4*)(H + (size_t)row * FF + col) = w;
;             }
	s_nop 0
	v_pk_mul_f32 v[38:39], v[34:35], v[38:39]
	v_pk_mul_f32 v[34:35], v[40:41], v[144:145] op_sel_hi:[1,0]
	s_nop 0
	v_mul_f32_e32 v40, 0xbfb8aa3b, v34
	v_min_f32_e32 v40, 0x42700000, v40
	v_exp_f32_e32 v41, v40
	v_mul_f32_e32 v40, 0xbfb8aa3b, v35
	v_min_f32_e32 v40, 0x42700000, v40
	v_exp_f32_e32 v40, v40
	s_nop 0
	v_pk_add_f32 v[40:41], v[40:41], 1.0 op_sel_hi:[1,0]
	s_nop 0
	v_mul_f32_e32 v46, v41, v40
	v_rcp_f32_e32 v46, v46
	s_nop 0
	v_pk_mul_f32 v[40:41], v[40:41], v[46:47] op_sel_hi:[1,0]
	s_nop 0
	v_pk_mul_f32 v[34:35], v[34:35], v[40:41]
	v_add_u32_e32 v46, 0x90, v156
	v_pk_mul_f32 v[40:41], v[36:37], v[34:35]
	v_cvt_pk_bf16_f32 v36, v38, v39
	v_mad_i64_i32 v[38:39], s[6:7], v46, s77, v[114:115]
	v_cvt_pk_bf16_f32 v34, v42, v43
	v_cvt_pk_bf16_f32 v35, v44, v45
	v_cvt_pk_bf16_f32 v37, v40, v41
	v_lshl_add_u64 v[38:39], v[38:39], 0, v[116:117]
	global_store_dwordx4 v[38:39], v[34:37], off
	s_nop 1
	v_mul_f32_e32 v34, 0xbfb8aa3b, v30
	v_min_f32_e32 v34, 0x42700000, v34
	v_exp_f32_e32 v35, v34
	v_mul_f32_e32 v34, 0xbfb8aa3b, v31
	v_min_f32_e32 v34, 0x42700000, v34
	v_exp_f32_e32 v34, v34
	s_nop 0
	v_pk_add_f32 v[34:35], v[34:35], 1.0 op_sel_hi:[1,0]
	s_nop 0
	v_mul_f32_e32 v36, v35, v34
	v_rcp_f32_e32 v36, v36
	s_nop 0
	v_pk_mul_f32 v[34:35], v[34:35], v[36:37] op_sel_hi:[1,0]
	s_nop 0
	v_pk_mul_f32 v[30:31], v[30:31], v[34:35]
	s_nop 0
	v_pk_mul_f32 v[26:27], v[26:27], v[30:31]
	v_pk_mul_f32 v[30:31], v[32:33], v[142:143] op_sel_hi:[1,0]
	s_nop 0
	v_mul_f32_e32 v32, 0xbfb8aa3b, v30
	v_min_f32_e32 v32, 0x42700000, v32
	v_exp_f32_e32 v33, v32
	v_mul_f32_e32 v32, 0xbfb8aa3b, v31
	v_min_f32_e32 v32, 0x42700000, v32
	v_exp_f32_e32 v32, v32
	s_nop 0
	v_pk_add_f32 v[32:33], v[32:33], 1.0 op_sel_hi:[1,0]
	s_nop 0
	v_mul_f32_e32 v34, v33, v32
	v_rcp_f32_e32 v34, v34
	s_nop 0
	v_pk_mul_f32 v[32:33], v[32:33], v[34:35] op_sel_hi:[1,0]
	s_nop 0
	v_pk_mul_f32 v[30:31], v[30:31], v[32:33]
	s_nop 0
	v_pk_mul_f32 v[28:29], v[28:29], v[30:31]
	v_mul_f32_e32 v30, 0xbfb8aa3b, v22
	v_min_f32_e32 v30, 0x42700000, v30
	v_exp_f32_e32 v31, v30
	v_mul_f32_e32 v30, 0xbfb8aa3b, v23
	v_min_f32_e32 v30, 0x42700000, v30
	v_exp_f32_e32 v30, v30
	s_nop 0
	v_pk_add_f32 v[30:31], v[30:31], 1.0 op_sel_hi:[1,0]
	s_nop 0
	v_mul_f32_e32 v32, v31, v30
	v_rcp_f32_e32 v32, v32
	s_nop 0
	v_pk_mul_f32 v[30:31], v[30:31], v[32:33] op_sel_hi:[1,0]
	s_nop 0
	v_pk_mul_f32 v[22:23], v[22:23], v[30:31]
	s_nop 0
	v_pk_mul_f32 v[22:23], v[18:19], v[22:23]
	v_pk_mul_f32 v[18:19], v[24:25], v[142:143] op_sel_hi:[1,0]
	s_nop 0
	v_mul_f32_e32 v24, 0xbfb8aa3b, v18
	v_min_f32_e32 v24, 0x42700000, v24
	v_exp_f32_e32 v25, v24
	v_mul_f32_e32 v24, 0xbfb8aa3b, v19
	v_min_f32_e32 v24, 0x42700000, v24
	v_exp_f32_e32 v24, v24
	s_nop 0
	v_pk_add_f32 v[24:25], v[24:25], 1.0 op_sel_hi:[1,0]
	s_nop 0
	v_mul_f32_e32 v30, v25, v24
	v_rcp_f32_e32 v30, v30
	s_nop 0
	v_pk_mul_f32 v[24:25], v[24:25], v[30:31] op_sel_hi:[1,0]
	s_nop 0
	v_pk_mul_f32 v[18:19], v[18:19], v[24:25]
	v_add_u32_e32 v30, 0xa0, v156
	v_pk_mul_f32 v[24:25], v[20:21], v[18:19]
	v_cvt_pk_bf16_f32 v20, v22, v23
	v_mad_i64_i32 v[22:23], s[6:7], v30, s77, v[114:115]
	v_cvt_pk_bf16_f32 v18, v26, v27
	v_cvt_pk_bf16_f32 v19, v28, v29
	v_cvt_pk_bf16_f32 v21, v24, v25
	v_lshl_add_u64 v[22:23], v[22:23], 0, v[116:117]
	global_store_dwordx4 v[22:23], v[18:21], off
	s_nop 1
	v_mul_f32_e32 v18, 0xbfb8aa3b, v14
	v_min_f32_e32 v18, 0x42700000, v18
	v_exp_f32_e32 v19, v18
	v_mul_f32_e32 v18, 0xbfb8aa3b, v15
	v_min_f32_e32 v18, 0x42700000, v18
	v_exp_f32_e32 v18, v18
	s_nop 0
	v_pk_add_f32 v[18:19], v[18:19], 1.0 op_sel_hi:[1,0]
	s_nop 0
	v_mul_f32_e32 v20, v19, v18
	v_rcp_f32_e32 v20, v20
	s_nop 0
	v_pk_mul_f32 v[18:19], v[18:19], v[20:21] op_sel_hi:[1,0]
	s_nop 0
	v_pk_mul_f32 v[14:15], v[14:15], v[18:19]
	s_nop 0
	v_pk_mul_f32 v[10:11], v[10:11], v[14:15]
	v_pk_mul_f32 v[14:15], v[16:17], v[140:141] op_sel_hi:[1,0]
	s_nop 0
	v_mul_f32_e32 v16, 0xbfb8aa3b, v14
	v_min_f32_e32 v16, 0x42700000, v16
	v_exp_f32_e32 v17, v16
	v_mul_f32_e32 v16, 0xbfb8aa3b, v15
	v_min_f32_e32 v16, 0x42700000, v16
	v_exp_f32_e32 v16, v16
	s_nop 0
	v_pk_add_f32 v[16:17], v[16:17], 1.0 op_sel_hi:[1,0]
	s_nop 0
	v_mul_f32_e32 v18, v17, v16
	v_rcp_f32_e32 v18, v18
	s_nop 0
	v_pk_mul_f32 v[16:17], v[16:17], v[18:19] op_sel_hi:[1,0]
	s_nop 0
	v_pk_mul_f32 v[14:15], v[14:15], v[16:17]
	s_nop 0
	v_pk_mul_f32 v[12:13], v[12:13], v[14:15]
	v_mul_f32_e32 v14, 0xbfb8aa3b, v6
	v_min_f32_e32 v14, 0x42700000, v14
	v_exp_f32_e32 v15, v14
	v_mul_f32_e32 v14, 0xbfb8aa3b, v7
	v_min_f32_e32 v14, 0x42700000, v14
	v_exp_f32_e32 v14, v14
	s_nop 0
	v_pk_add_f32 v[14:15], v[14:15], 1.0 op_sel_hi:[1,0]
	s_nop 0
	v_mul_f32_e32 v16, v15, v14
	v_rcp_f32_e32 v16, v16
	s_nop 0
	v_pk_mul_f32 v[14:15], v[14:15], v[16:17] op_sel_hi:[1,0]
	s_nop 0
	v_pk_mul_f32 v[6:7], v[6:7], v[14:15]
	s_nop 0
	v_pk_mul_f32 v[6:7], v[2:3], v[6:7]
	v_pk_mul_f32 v[2:3], v[8:9], v[140:141] op_sel_hi:[1,0]
	s_nop 0
	v_mul_f32_e32 v8, 0xbfb8aa3b, v2
	v_min_f32_e32 v8, 0x42700000, v8
	v_exp_f32_e32 v9, v8
	v_mul_f32_e32 v8, 0xbfb8aa3b, v3
	v_min_f32_e32 v8, 0x42700000, v8
	v_exp_f32_e32 v8, v8
	s_nop 0
	v_pk_add_f32 v[8:9], v[8:9], 1.0 op_sel_hi:[1,0]
	s_nop 0
	v_mul_f32_e32 v14, v9, v8
	v_rcp_f32_e32 v14, v14
	s_nop 0
	v_pk_mul_f32 v[8:9], v[8:9], v[14:15] op_sel_hi:[1,0]
	s_nop 0
	v_pk_mul_f32 v[2:3], v[2:3], v[8:9]
	v_add_u32_e32 v14, 0xb0, v156
	v_pk_mul_f32 v[8:9], v[4:5], v[2:3]
	v_cvt_pk_bf16_f32 v4, v6, v7
	v_mad_i64_i32 v[6:7], s[6:7], v14, s77, v[114:115]
	v_cvt_pk_bf16_f32 v2, v10, v11
	v_cvt_pk_bf16_f32 v3, v12, v13
	v_cvt_pk_bf16_f32 v5, v8, v9
	v_lshl_add_u64 v[6:7], v[6:7], 0, v[116:117]
	s_mov_b64 s[6:7], -1
	global_store_dwordx4 v[6:7], v[2:5], off
	s_cbranch_vccnz .LBB0_663
	s_andn2_b64 vcc, exec, s[0:1]
	s_cbranch_vccnz .LBB0_662
	s_barrier
	s_branch .LBB0_662

; template <int MASK> __global__ void __launch_bounds__(512, 2) mega_fwd(Args a) {
;     extern __shared__ __attribute__((aligned(16))) unsigned char lds_raw[];
	.amdhsa_kernel _Z8mega_fwdILi511EEv4Args
		.amdhsa_group_segment_fixed_size 0
		.amdhsa_private_segment_fixed_size 0
		.amdhsa_kernarg_size 528
		.amdhsa_user_sgpr_count 2
		.amdhsa_user_sgpr_dispatch_ptr 0
		.amdhsa_user_sgpr_queue_ptr 0
		.amdhsa_user_sgpr_kernarg_segment_ptr 1
		.amdhsa_user_sgpr_dispatch_id 0
		.amdhsa_user_sgpr_kernarg_preload_length 0
		.amdhsa_user_sgpr_kernarg_preload_offset 0
		.amdhsa_user_sgpr_private_segment_size 0
		.amdhsa_uses_dynamic_stack 0
		.amdhsa_enable_private_segment 0
		.amdhsa_system_sgpr_workgroup_id_x 1
		.amdhsa_system_sgpr_workgroup_id_y 0
		.amdhsa_system_sgpr_workgroup_id_z 0
		.amdhsa_system_sgpr_workgroup_info 0
		.amdhsa_system_vgpr_workitem_id 2
		.amdhsa_next_free_vgpr 256
		.amdhsa_next_free_sgpr 102
		.amdhsa_accum_offset 256
		.amdhsa_reserve_vcc 1
		.amdhsa_float_round_mode_32 0
		.amdhsa_float_round_mode_16_64 0
		.amdhsa_float_denorm_mode_32 3
		.amdhsa_float_denorm_mode_16_64 3
		.amdhsa_dx10_clamp 1
		.amdhsa_ieee_mode 1
		.amdhsa_fp16_overflow 0
		.amdhsa_tg_split 0
		.amdhsa_exception_fp_ieee_invalid_op 0
		.amdhsa_exception_fp_denorm_src 0
		.amdhsa_exception_fp_ieee_div_zero 0
		.amdhsa_exception_fp_ieee_overflow 0
		.amdhsa_exception_fp_ieee_underflow 0
		.amdhsa_exception_fp_ieee_inexact 0
		.amdhsa_exception_int_div_zero 0
	.end_amdhsa_kernel

; template <int MASK> __global__ void __launch_bounds__(512, 2) mega_fwd(Args a) {
;     extern __shared__ __attribute__((aligned(16))) unsigned char lds_raw[];
amdhsa.kernels:
  - .agpr_count:     0
    .args:
      - .offset:         0
        .size:           272
        .value_kind:     by_value
      - .offset:         272
        .size:           4
        .value_kind:     hidden_block_count_x
      - .offset:         276
        .size:           4
        .value_kind:     hidden_block_count_y
      - .offset:         280
        .size:           4
        .value_kind:     hidden_block_count_z
      - .offset:         284
        .size:           2
        .value_kind:     hidden_group_size_x
      - .offset:         286
        .size:           2
        .value_kind:     hidden_group_size_y
      - .offset:         288
        .size:           2
        .value_kind:     hidden_group_size_z
      - .offset:         290
        .size:           2
        .value_kind:     hidden_remainder_x
      - .offset:         292
        .size:           2
        .value_kind:     hidden_remainder_y
      - .offset:         294
        .size:           2
        .value_kind:     hidden_remainder_z
      - .offset:         312
        .size:           8
        .value_kind:     hidden_global_offset_x
      - .offset:         320
        .size:           8
        .value_kind:     hidden_global_offset_y
      - .offset:         328
        .size:           8
        .value_kind:     hidden_global_offset_z
      - .offset:         336
        .size:           2
        .value_kind:     hidden_grid_dims
      - .offset:         360
        .size:           8
        .value_kind:     hidden_multigrid_sync_arg
      - .offset:         392
        .size:           4
        .value_kind:     hidden_dynamic_lds_size
    .group_segment_fixed_size: 0
    .kernarg_segment_align: 8
    .kernarg_segment_size: 528
    .language:       OpenCL C
    .language_version:
      - 2
      - 0
    .max_flat_workgroup_size: 512
    .name:           _Z8mega_fwdILi511EEv4Args
    .private_segment_fixed_size: 0
    .sgpr_count:     108
    .sgpr_spill_count: 197
    .symbol:         _Z8mega_fwdILi511EEv4Args.kd
    .uniform_work_group_size: 1
    .uses_dynamic_stack: false
    .vgpr_count:     256
    .vgpr_spill_count: 0
    .wavefront_size: 64
